# NSA selection-branch loop: running-max subtraction folded into the QK MFMA C-init (per-query -inf for unselected blocks) and sum-triggered rescale (row-max chain only on first tile)
# speedup vs baseline: 1.0045x; 1.0045x over previous
.LBB0_4380:
	s_or_b64 exec, exec, s[2:3]
	s_load_dwordx4 s[4:7], s[0:1], 0x1b8
	v_mov_b32_e32 v0, v169
	s_lshl_b64 s[10:11], s[50:51], 21
	s_waitcnt lgkmcnt(0)
	s_add_u32 s2, s4, s10
	v_add_u32_e32 v3, s70, v0
	v_ashrrev_i32_e32 v2, 31, v3
	s_addc_u32 s3, s5, s11
	s_lshl_b32 s8, s74, 7
	v_lshrrev_b32_e32 v2, 29, v2
	s_add_u32 s2, s2, s8
	v_add_u32_e32 v4, v3, v2
	s_addc_u32 s3, s3, 0
	v_ashrrev_i32_e32 v2, 3, v4
	v_and_b32_e32 v4, 0x1ffffff8, v4
	s_add_u32 s9, s6, s10
	v_sub_u32_e32 v3, v3, v4
	s_addc_u32 s12, s7, s11
	s_waitcnt vmcnt(10)
	v_lshlrev_b32_e32 v122, 3, v3
	v_ashrrev_i32_e32 v3, 31, v2
	s_add_u32 s8, s9, s8
	s_waitcnt vmcnt(9)
	v_lshlrev_b64 v[124:125], 9, v[2:3]
	v_ashrrev_i32_e32 v123, 31, v122
	s_addc_u32 s9, s12, 0
	v_lshl_add_u64 v[4:5], s[2:3], 0, v[124:125]
	v_lshlrev_b64 v[6:7], 1, v[122:123]
	v_lshl_add_u64 v[4:5], v[4:5], 0, v[6:7]
	v_lshl_add_u64 v[8:9], s[8:9], 0, v[124:125]
	v_lshl_add_u64 v[6:7], v[8:9], 0, v[6:7]
	global_load_dwordx4 v[112:115], v[4:5], off
	global_load_dwordx4 v[116:119], v[6:7], off
	s_sub_i32 s2, 0x103f, s72
	s_ashr_i32 s3, s2, 31
	s_lshr_b32 s3, s3, 26
	s_add_i32 s2, s2, s3
	s_ashr_i32 s8, s2, 6
	s_ashr_i32 s2, s75, 6
	s_add_i32 s3, s2, 1
	s_min_i32 s14, s3, s8
	s_cmp_lt_i32 s14, 1
	v_mul_lo_u32 v130, v2, s63
	v_mul_lo_u32 v131, v2, s64
	s_barrier
	s_cbranch_scc1 .LBB0_4390
	v_bfe_u32 v2, v0, 5, 1
	v_and_b32_e32 v3, 31, v0
	s_sub_i32 s3, s67, s73
	v_or_b32_e32 v132, s48, v3
	v_lshlrev_b32_e32 v133, 2, v2
	v_mul_u32_u24_e32 v66, 0x48, v3
	v_lshlrev_b32_e32 v135, 4, v2
	v_lshl_add_u64 v[2:3], s[10:11], 0, v[124:125]
	s_and_b32 s3, s3, 3
	v_lshrrev_b32_e32 v4, 2, v0
	v_lshl_or_b32 v2, s3, 7, v2
	s_ashr_i32 s3, s2, 31
	v_and_or_b32 v4, v4, 3, v133
	v_lshl_add_u64 v[2:3], v[122:123], 1, v[2:3]
	s_add_u32 s2, s2, 1
	v_mul_u32_u24_e32 v134, 0xc0, v4
	v_lshl_add_u64 v[4:5], s[4:5], 0, v[2:3]
	v_lshl_add_u64 v[2:3], s[6:7], 0, v[2:3]
	s_addc_u32 s3, s3, 0
	s_ashr_i32 s9, s8, 31
	v_and_b32_e32 v64, 16, v0
	v_lshlrev_b32_e32 v0, 2, v0
	v_lshl_add_u64 v[128:129], v[2:3], 0, s[36:37]
	v_mov_b64_e32 v[2:3], s[8:9]
	v_and_b32_e32 v65, 12, v0
	v_cmp_lt_i64_e32 vcc, s[2:3], v[2:3]
	v_mov_b32_e32 v30, v1
	v_mov_b32_e32 v31, v1
	v_lshl_add_u64 v[126:127], v[4:5], 0, s[36:37]
	s_and_b64 s[12:13], vcc, exec
	v_mov_b32_e32 v0, v1
	v_mov_b32_e32 v2, v1
	v_mov_b32_e32 v3, v1
	v_mov_b32_e32 v4, v1
	v_mov_b32_e32 v5, v1
	v_mov_b32_e32 v6, v1
	v_mov_b32_e32 v7, v1
	v_mov_b32_e32 v8, v1
	v_mov_b32_e32 v9, v1
	v_mov_b32_e32 v10, v1
	v_mov_b32_e32 v11, v1
	v_mov_b32_e32 v12, v1
	v_mov_b32_e32 v13, v1
	v_mov_b32_e32 v14, v1
	v_mov_b32_e32 v15, v1
	v_mov_b32_e32 v16, v1
	v_mov_b32_e32 v17, v1
	v_mov_b32_e32 v18, v1
	v_mov_b32_e32 v19, v1
	v_mov_b32_e32 v20, v1
	v_mov_b32_e32 v21, v1
	v_mov_b32_e32 v22, v1
	v_mov_b32_e32 v23, v1
	v_mov_b32_e32 v24, v1
	v_mov_b32_e32 v25, v1
	v_mov_b32_e32 v26, v1
	v_mov_b32_e32 v27, v1
	v_mov_b32_e32 v28, v1
	v_mov_b32_e32 v29, v1
	v_lshlrev_b32_e32 v136, 1, v66
	v_lshlrev_b32_e32 v137, 1, v64
	v_lshlrev_b32_e32 v138, 1, v65
	s_waitcnt vmcnt(2)
	v_mov_b64_e32 v[94:95], v[30:31]
	s_cselect_b32 s9, s2, s8
	v_mov_b32_e32 v189, 0
	v_mov_b32_e32 v139, 0xf149f2ca
	s_mov_b32 s98, 1
	v_mov_b32_e32 v212, 0
	v_mov_b32_e32 v213, 0
	v_mov_b32_e32 v214, 0
	v_mov_b32_e32 v215, 0
	v_mov_b32_e32 v216, 0
	v_mov_b32_e32 v217, 0
	v_mov_b32_e32 v218, 0
	v_mov_b32_e32 v219, 0
	v_mov_b32_e32 v220, 0
	v_mov_b32_e32 v221, 0
	v_mov_b32_e32 v222, 0
	v_mov_b32_e32 v223, 0
	v_mov_b32_e32 v224, 0
	v_mov_b32_e32 v225, 0
	v_mov_b32_e32 v226, 0
	v_mov_b32_e32 v227, 0
	v_mov_b32_e32 v228, 0
	v_mov_b32_e32 v229, v139
	s_mov_b64 s[2:3], 0
	s_mov_b32 s15, 63
	v_mov_b64_e32 v[92:93], v[28:29]
	v_mov_b64_e32 v[90:91], v[26:27]
	v_mov_b64_e32 v[88:89], v[24:25]
	v_mov_b64_e32 v[86:87], v[22:23]
	v_mov_b64_e32 v[84:85], v[20:21]
	v_mov_b64_e32 v[82:83], v[18:19]
	v_mov_b64_e32 v[80:81], v[16:17]
	v_mov_b64_e32 v[78:79], v[14:15]
	v_mov_b64_e32 v[76:77], v[12:13]
	v_mov_b64_e32 v[74:75], v[10:11]
	v_mov_b64_e32 v[72:73], v[8:9]
	v_mov_b64_e32 v[70:71], v[6:7]
	v_mov_b64_e32 v[68:69], v[4:5]
	v_mov_b64_e32 v[66:67], v[2:3]
	v_mov_b64_e32 v[64:65], v[0:1]

.LBB0_4386:
	s_nop 8
	s_cmp_eq_u32 s98, 0
	s_cbranch_scc1 .LBB0_4388
	v_max3_f32 v0, v96, s66, v97
	v_max3_f32 v0, v0, v98, v99
	v_max3_f32 v0, v0, v100, v101
	v_max3_f32 v0, v0, v102, v103
	v_max3_f32 v0, v0, v104, v105
	v_max3_f32 v0, v0, v106, v107
	v_max3_f32 v0, v0, v108, v109
	v_max3_f32 v0, v0, v110, v111
	v_max3_f32 v0, v0, v2, v3
	v_max3_f32 v0, v0, v4, v5
	v_max3_f32 v0, v0, v6, v7
	v_max3_f32 v0, v0, v8, v9
	v_max3_f32 v0, v0, v10, v11
	v_max3_f32 v0, v0, v12, v13
	v_max3_f32 v0, v0, v14, v15
	v_max3_f32 v20, v0, v16, v17
	ds_bpermute_b32 v21, v175, v20
	v_lshrrev_b64 v[18:19], s2, v[120:121]
	v_and_b32_e32 v0, 1, v18
	v_cmp_eq_u64_e64 s[2:3], 0, v[0:1]
	s_waitcnt lgkmcnt(0)
	v_max_f32_e32 v18, v21, v21
	v_max_f32_e32 v18, v20, v18
	v_cndmask_b32_e64 v0, v18, v185, s[2:3]
	v_add_f32_e32 v18, 0x41000000, v229
	v_cmp_gt_f32_e32 vcc, v0, v18
	s_cbranch_vccz .LBB0_4388
	v_max_f32_e32 v0, v0, v0
	v_max_f32_e32 v230, v229, v229
	v_max_f32_e32 v230, v230, v0
	v_sub_f32_e32 v231, v230, v228
	v_sub_f32_e32 v0, v229, v230
	v_exp_f32_e32 v0, v0
	s_nop 0
	v_pk_mul_f32 v[94:95], v[94:95], v[0:1] op_sel_hi:[1,0]
	v_pk_mul_f32 v[92:93], v[92:93], v[0:1] op_sel_hi:[1,0]
	v_pk_mul_f32 v[90:91], v[90:91], v[0:1] op_sel_hi:[1,0]
	v_pk_mul_f32 v[88:89], v[88:89], v[0:1] op_sel_hi:[1,0]
	v_pk_mul_f32 v[86:87], v[86:87], v[0:1] op_sel_hi:[1,0]
	v_pk_mul_f32 v[84:85], v[84:85], v[0:1] op_sel_hi:[1,0]
	v_pk_mul_f32 v[82:83], v[82:83], v[0:1] op_sel_hi:[1,0]
	v_pk_mul_f32 v[80:81], v[80:81], v[0:1] op_sel_hi:[1,0]
	v_pk_mul_f32 v[78:79], v[78:79], v[0:1] op_sel_hi:[1,0]
	v_pk_mul_f32 v[76:77], v[76:77], v[0:1] op_sel_hi:[1,0]
	v_pk_mul_f32 v[74:75], v[74:75], v[0:1] op_sel_hi:[1,0]
	v_pk_mul_f32 v[72:73], v[72:73], v[0:1] op_sel_hi:[1,0]
	v_pk_mul_f32 v[70:71], v[70:71], v[0:1] op_sel_hi:[1,0]
	v_pk_mul_f32 v[68:69], v[68:69], v[0:1] op_sel_hi:[1,0]
	v_pk_mul_f32 v[66:67], v[66:67], v[0:1] op_sel_hi:[1,0]
	v_pk_mul_f32 v[64:65], v[64:65], v[0:1] op_sel_hi:[1,0]
	v_mul_f32_e32 v189, v189, v0
	v_mov_b32_e32 v139, v231
	v_xor_b32_e32 v230, 0x80000000, v231
	v_cmp_lt_f32_e32 vcc, 0xf0a18f08, v231
	s_nop 1
	v_cndmask_b32_e32 v230, 0, v230, vcc
	v_add_f32_e32 v229, v231, v230
	v_sub_f32_e32 v231, v230, v228
	v_mov_b32_e32 v228, v230
	v_add_f32_e32 v2, v231, v2
	v_add_f32_e32 v3, v231, v3
	v_add_f32_e32 v4, v231, v4
	v_add_f32_e32 v5, v231, v5
	v_add_f32_e32 v6, v231, v6
	v_add_f32_e32 v7, v231, v7
	v_add_f32_e32 v8, v231, v8
	v_add_f32_e32 v9, v231, v9
	v_add_f32_e32 v10, v231, v10
	v_add_f32_e32 v11, v231, v11
	v_add_f32_e32 v12, v231, v12
	v_add_f32_e32 v13, v231, v13
	v_add_f32_e32 v14, v231, v14
	v_add_f32_e32 v15, v231, v15
	v_add_f32_e32 v16, v231, v16
	v_add_f32_e32 v17, v231, v17
	v_add_f32_e32 v96, v231, v96
	v_add_f32_e32 v97, v231, v97
	v_add_f32_e32 v98, v231, v98
	v_add_f32_e32 v99, v231, v99
	v_add_f32_e32 v100, v231, v100
	v_add_f32_e32 v101, v231, v101
	v_add_f32_e32 v102, v231, v102
	v_add_f32_e32 v103, v231, v103
	v_add_f32_e32 v104, v231, v104
	v_add_f32_e32 v105, v231, v105
	v_add_f32_e32 v106, v231, v106
	v_add_f32_e32 v107, v231, v107
	v_add_f32_e32 v108, v231, v108
	v_add_f32_e32 v109, v231, v109
	v_add_f32_e32 v110, v231, v110
	v_add_f32_e32 v111, v231, v111
	v_cndmask_b32_e32 v139, 0, v139, vcc
.LBB0_4388:
	v_add_u32_e32 v19, s20, v134
	v_exp_f32_e32 v18, v96
	v_add3_u32 v22, v19, v137, v138
	v_exp_f32_e32 v19, v97
	v_exp_f32_e32 v21, v98
	v_exp_f32_e32 v23, v99
	v_add_f32_e32 v20, 0, v18
	v_exp_f32_e32 v24, v100
	v_add_f32_e32 v20, v19, v20
	v_exp_f32_e32 v25, v101
	v_add_f32_e32 v20, v21, v20
	v_exp_f32_e32 v26, v102
	v_add_f32_e32 v20, v23, v20
	v_exp_f32_e32 v27, v103
	v_add_f32_e32 v20, v24, v20
	v_exp_f32_e32 v28, v104
	v_add_f32_e32 v20, v25, v20
	v_exp_f32_e32 v29, v105
	v_add_f32_e32 v20, v26, v20
	v_exp_f32_e32 v30, v106
	v_add_f32_e32 v20, v27, v20
	v_exp_f32_e32 v31, v107
	v_add_f32_e32 v20, v28, v20
	v_exp_f32_e32 v96, v108
	v_add_f32_e32 v20, v29, v20
	v_exp_f32_e32 v97, v109
	v_add_f32_e32 v20, v30, v20
	v_exp_f32_e32 v98, v110
	v_add_f32_e32 v20, v31, v20
	v_exp_f32_e32 v99, v111
	v_add_f32_e32 v20, v96, v20
	v_exp_f32_e32 v100, v2
	v_add_f32_e32 v2, v97, v20
	v_exp_f32_e32 v101, v3
	v_add_f32_e32 v2, v98, v2
	v_exp_f32_e32 v102, v4
	v_add_f32_e32 v2, v99, v2
	v_exp_f32_e32 v103, v5
	v_add_f32_e32 v2, v100, v2
	v_exp_f32_e32 v104, v6
	v_add_f32_e32 v2, v101, v2
	v_add_f32_e32 v2, v102, v2
	v_add_f32_e32 v2, v103, v2
	v_add_f32_e32 v105, v104, v2
	v_exp_f32_e32 v106, v7
	v_exp_f32_e32 v107, v8
	v_exp_f32_e32 v108, v9
	ds_read_b64_tr_b16 v[2:3], v22 offset:9216
	ds_read_b64_tr_b16 v[4:5], v22 offset:10752
	v_exp_f32_e32 v109, v10
	v_cvt_pk_bf16_f32 v7, v21, v23
	v_cvt_pk_bf16_f32 v6, v18, v19
	ds_read_b64_tr_b16 v[20:21], v22 offset:10816
	ds_read_b64_tr_b16 v[18:19], v22 offset:9280
	v_cvt_pk_bf16_f32 v9, v26, v27
	v_cvt_pk_bf16_f32 v8, v24, v25
	v_mov_b32_e32 v24, v11
	s_waitcnt lgkmcnt(2)
	v_mfma_f32_32x32x16_bf16 v[64:79], v[2:5], v[6:9], v[64:79]
	v_add_f32_e32 v2, v106, v105
	v_add_f32_e32 v2, v107, v2
	v_add_f32_e32 v2, v108, v2
	v_add_f32_e32 v23, v109, v2
	ds_read_b64_tr_b16 v[2:3], v22 offset:12288
	ds_read_b64_tr_b16 v[4:5], v22 offset:13824
	v_exp_f32_e32 v25, v12
	s_waitcnt lgkmcnt(2)
	v_mfma_f32_32x32x16_bf16 v[80:95], v[18:21], v[6:9], v[80:95]
	ds_read_b64_tr_b16 v[20:21], v22 offset:13888
	ds_read_b64_tr_b16 v[18:19], v22 offset:12352
	v_cvt_pk_bf16_f32 v9, v98, v99
	v_cvt_pk_bf16_f32 v8, v96, v97
	v_cvt_pk_bf16_f32 v7, v30, v31
	v_cvt_pk_bf16_f32 v6, v28, v29
	v_exp_f32_e32 v15, v15
	s_add_i32 s15, s15, 64
	s_waitcnt lgkmcnt(2)
	v_mfma_f32_32x32x16_bf16 v[64:79], v[2:5], v[6:9], v[64:79]
	v_exp_f32_e32 v26, v13
	v_exp_f32_e32 v14, v14
	ds_read_b64_tr_b16 v[2:3], v22 offset:15360
	ds_read_b64_tr_b16 v[4:5], v22 offset:16896
	ds_read_b64_tr_b16 v[12:13], v22 offset:16960
	ds_read_b64_tr_b16 v[10:11], v22 offset:15424
	v_lshl_add_u64 v[126:127], v[126:127], 0, s[36:37]
	s_waitcnt lgkmcnt(4)
	v_mfma_f32_32x32x16_bf16 v[80:95], v[18:21], v[6:9], v[80:95]
	v_cvt_pk_bf16_f32 v9, v107, v108
	v_cvt_pk_bf16_f32 v8, v104, v106
	v_cvt_pk_bf16_f32 v7, v102, v103
	v_cvt_pk_bf16_f32 v6, v100, v101
	s_cmp_eq_u32 s9, s12
	v_lshl_add_u64 v[128:129], v[128:129], 0, s[36:37]
	s_waitcnt lgkmcnt(2)
	v_mfma_f32_32x32x16_bf16 v[64:79], v[2:5], v[6:9], v[64:79]
	v_exp_f32_e32 v16, v16
	v_exp_f32_e32 v0, v17
	ds_read_b64_tr_b16 v[2:3], v22 offset:18432
	ds_read_b64_tr_b16 v[4:5], v22 offset:19968
	v_exp_f32_e32 v17, v24
	s_waitcnt lgkmcnt(2)
	v_mfma_f32_32x32x16_bf16 v[80:95], v[10:13], v[6:9], v[80:95]
	ds_read_b64_tr_b16 v[12:13], v22 offset:20032
	ds_read_b64_tr_b16 v[10:11], v22 offset:18496
	v_cvt_pk_bf16_f32 v9, v16, v0
	v_cvt_pk_bf16_f32 v8, v14, v15
	v_cvt_pk_bf16_f32 v7, v25, v26
	v_cvt_pk_bf16_f32 v6, v109, v17
	s_waitcnt lgkmcnt(2)
	s_nop 0
	v_mfma_f32_32x32x16_bf16 v[64:79], v[2:5], v[6:9], v[64:79]
	v_add_f32_e32 v2, v17, v23
	v_add_f32_e32 v2, v25, v2
	v_add_f32_e32 v2, v26, v2
	v_add_f32_e32 v2, v14, v2
	v_add_f32_e32 v2, v15, v2
	v_add_f32_e32 v2, v16, v2
	v_add_f32_e32 v0, v0, v2
	s_waitcnt lgkmcnt(0)
	v_mfma_f32_32x32x16_bf16 v[80:95], v[10:13], v[6:9], v[80:95]
	v_add_f32_e32 v189, v189, v0
	s_mov_b32 s98, 0
	v_cmp_lt_f32_e32 vcc, 0x49800000, v0
	s_cbranch_vccz .Lsgphase15_35711
	s_nop 7
	s_nop 4
	v_mov_b32_e32 v230, v0
	v_mov_b32_e32 v231, v0
	s_nop 1
	v_permlane32_swap_b32_e32 v230, v231
	v_max_f32_e32 v230, v230, v231
	v_max_f32_e32 v230, 1.0, v230
	v_log_f32_e32 v230, v230
	s_nop 0
	v_sub_f32_e32 v232, 0, v230
	v_exp_f32_e32 v232, v232
	s_nop 0
	v_pk_mul_f32 v[94:95], v[94:95], v[232:233] op_sel_hi:[1,0]
	v_pk_mul_f32 v[92:93], v[92:93], v[232:233] op_sel_hi:[1,0]
	v_pk_mul_f32 v[90:91], v[90:91], v[232:233] op_sel_hi:[1,0]
	v_pk_mul_f32 v[88:89], v[88:89], v[232:233] op_sel_hi:[1,0]
	v_pk_mul_f32 v[86:87], v[86:87], v[232:233] op_sel_hi:[1,0]
	v_pk_mul_f32 v[84:85], v[84:85], v[232:233] op_sel_hi:[1,0]
	v_pk_mul_f32 v[82:83], v[82:83], v[232:233] op_sel_hi:[1,0]
	v_pk_mul_f32 v[80:81], v[80:81], v[232:233] op_sel_hi:[1,0]
	v_pk_mul_f32 v[78:79], v[78:79], v[232:233] op_sel_hi:[1,0]
	v_pk_mul_f32 v[76:77], v[76:77], v[232:233] op_sel_hi:[1,0]
	v_pk_mul_f32 v[74:75], v[74:75], v[232:233] op_sel_hi:[1,0]
	v_pk_mul_f32 v[72:73], v[72:73], v[232:233] op_sel_hi:[1,0]
	v_pk_mul_f32 v[70:71], v[70:71], v[232:233] op_sel_hi:[1,0]
	v_pk_mul_f32 v[68:69], v[68:69], v[232:233] op_sel_hi:[1,0]
	v_pk_mul_f32 v[66:67], v[66:67], v[232:233] op_sel_hi:[1,0]
	v_pk_mul_f32 v[64:65], v[64:65], v[232:233] op_sel_hi:[1,0]
	v_mul_f32_e32 v189, v189, v232
	v_sub_f32_e32 v228, v228, v230
	v_xor_b32_e32 v139, 0x80000000, v228
.Lsgphase15_35711:
	s_cbranch_scc1 .LBB0_4391
	s_mov_b64 s[2:3], s[12:13]
	s_branch .LBB0_4382
